# in-proj LDS-DMA feed: each K-step's batch issued as one burst right behind the barrier that frees its stage (full-K-step in-flight window)
# baseline (speedup 1.0000x reference)
; template <int EPI>
; DI void gemm_phase(const P& p, int l, const u16* __restrict__ A, const u16* __restrict__ Bt, int mpx, char* lds) {
;     ...
;   {
;   const int lane = tid & 63, w = tid >> 6, r = lane & 15, g = lane >> 4, wm = w >> 2, wn = w & 3;
;   __syncthreads();
;   GLOAD(Ag, Bg, 64)
;   __builtin_amdgcn_sched_barrier(0);
;   GCOMPUTE_KS(As0, Bs0, 0)
;   __builtin_amdgcn_sched_barrier(0);
;   GSTORE(As1, Bs1)
;   GLOAD(Ag, Bg, 128)
;   __builtin_amdgcn_sched_barrier(0);
;   GCOMPUTE_KS(As0, Bs0, 1)
;   __builtin_amdgcn_sched_barrier(0);
.Lrot_in_nofirst:
	s_add_i32 s48, s48, 1
	s_and_b32 s48, s48, 15
	s_lshl_b32 s2, s48, 7
	s_add_u32 s44, s40, s2
	s_addc_u32 s45, s41, 0
	s_add_u32 s42, s0, s2
	s_addc_u32 s43, s1, 0
	s_and_b32 s2, s84, 7
	s_lshl_b32 s2, s2, 8
	s_add_u32 s62, s58, s2
	s_addc_u32 s63, s59, 0
	s_add_u32 s64, s60, s2
	s_addc_u32 s65, s61, 0
	s_add_i32 m0, s47, 0x10020
	s_nop 0
	global_load_lds_dwordx4 v162, s[44:45]
	s_add_i32 m0, s47, 0x12020
	s_nop 0
	global_load_lds_dwordx4 v163, s[44:45]
	s_add_i32 m0, s47, 0x14020
	s_nop 0
	global_load_lds_dwordx4 v164, s[44:45]
	s_add_i32 m0, s47, 0x16020
	s_nop 0
	global_load_lds_dwordx4 v165, s[44:45]
	s_add_i32 m0, s47, 0x18020
	s_nop 0
	global_load_lds_dwordx4 v162, s[42:43]
	s_add_i32 m0, s47, 0x1a020
	s_nop 0
	global_load_lds_dwordx4 v163, s[42:43]
	s_add_i32 m0, s47, 0x1c020
	s_nop 0
	global_load_lds_dwordx4 v164, s[42:43]
	s_add_i32 m0, s47, 0x1e020
	s_nop 0
	global_load_lds_dwordx4 v165, s[42:43]
	ds_read_b128 v[212:215], v204 offset:32768
	ds_read_b128 v[216:219], v204 offset:34816
	ds_read_b128 v[220:223], v204 offset:36864
	ds_read_b128 v[234:237], v204 offset:38912
	ds_read_b128 v[238:241], v205
	ds_read_b128 v[242:245], v205 offset:2048
	ds_read_b128 v[246:249], v205 offset:4096
	ds_read_b128 v[250:253], v205 offset:6144
	s_waitcnt lgkmcnt(3)
	v_mfma_f32_16x16x32_bf16 v[6:9], v[238:241], v[212:215], 0
	v_mfma_f32_16x16x32_bf16 v[10:13], v[238:241], v[216:219], 0
	v_mfma_f32_16x16x32_bf16 v[14:17], v[238:241], v[220:223], 0
	v_mfma_f32_16x16x32_bf16 v[18:21], v[238:241], v[234:237], 0
	ds_read_b128 v[238:241], v205 offset:8192
	s_waitcnt lgkmcnt(3)
	v_mfma_f32_16x16x32_bf16 v[22:25], v[242:245], v[212:215], 0
	v_mfma_f32_16x16x32_bf16 v[26:29], v[242:245], v[216:219], 0
	v_mfma_f32_16x16x32_bf16 v[30:33], v[242:245], v[220:223], 0
	v_mfma_f32_16x16x32_bf16 v[34:37], v[242:245], v[234:237], 0
	ds_read_b128 v[242:245], v205 offset:10240
	ds_read_b128 v[130:133], v206 offset:32768
	s_waitcnt lgkmcnt(4)
	v_mfma_f32_16x16x32_bf16 v[38:41], v[246:249], v[212:215], 0
	v_mfma_f32_16x16x32_bf16 v[42:45], v[246:249], v[216:219], 0
	v_mfma_f32_16x16x32_bf16 v[46:49], v[246:249], v[220:223], 0
	v_mfma_f32_16x16x32_bf16 v[50:53], v[246:249], v[234:237], 0
	ds_read_b128 v[246:249], v205 offset:12288
	ds_read_b128 v[134:137], v206 offset:34816
	s_waitcnt lgkmcnt(5)
	v_mfma_f32_16x16x32_bf16 v[54:57], v[250:253], v[212:215], 0
	v_mfma_f32_16x16x32_bf16 v[58:61], v[250:253], v[216:219], 0
	v_mfma_f32_16x16x32_bf16 v[62:65], v[250:253], v[220:223], 0
	v_mfma_f32_16x16x32_bf16 v[66:69], v[250:253], v[234:237], 0
	ds_read_b128 v[250:253], v205 offset:14336
	ds_read_b128 v[138:141], v206 offset:36864
	s_waitcnt lgkmcnt(6)
	v_mfma_f32_16x16x32_bf16 v[70:73], v[238:241], v[212:215], 0
	v_mfma_f32_16x16x32_bf16 v[74:77], v[238:241], v[216:219], 0
	v_mfma_f32_16x16x32_bf16 v[78:81], v[238:241], v[220:223], 0
	v_mfma_f32_16x16x32_bf16 v[82:85], v[238:241], v[234:237], 0
	ds_read_b128 v[238:241], v207
	ds_read_b128 v[142:145], v206 offset:38912
	s_waitcnt lgkmcnt(7)
	v_mfma_f32_16x16x32_bf16 v[86:89], v[242:245], v[212:215], 0
	v_mfma_f32_16x16x32_bf16 v[90:93], v[242:245], v[216:219], 0
	v_mfma_f32_16x16x32_bf16 v[94:97], v[242:245], v[220:223], 0
	v_mfma_f32_16x16x32_bf16 v[98:101], v[242:245], v[234:237], 0
	ds_read_b128 v[242:245], v207 offset:2048
	s_waitcnt lgkmcnt(6)
	v_mfma_f32_16x16x32_bf16 v[102:105], v[246:249], v[212:215], 0
	v_mfma_f32_16x16x32_bf16 v[106:109], v[246:249], v[216:219], 0
	v_mfma_f32_16x16x32_bf16 v[110:113], v[246:249], v[220:223], 0
	v_mfma_f32_16x16x32_bf16 v[114:117], v[246:249], v[234:237], 0
	ds_read_b128 v[246:249], v207 offset:4096
	s_waitcnt lgkmcnt(5)
	v_mfma_f32_16x16x32_bf16 v[118:121], v[250:253], v[212:215], 0
	v_mfma_f32_16x16x32_bf16 v[122:125], v[250:253], v[216:219], 0
	v_mfma_f32_16x16x32_bf16 v[126:129], v[250:253], v[220:223], 0
	v_mfma_f32_16x16x32_bf16 v[2:5], v[250:253], v[234:237], 0
	ds_read_b128 v[250:253], v207 offset:6144
	s_waitcnt lgkmcnt(3)
	v_mfma_f32_16x16x32_bf16 v[6:9], v[238:241], v[130:133], v[6:9]
	v_mfma_f32_16x16x32_bf16 v[10:13], v[238:241], v[134:137], v[10:13]
	v_mfma_f32_16x16x32_bf16 v[14:17], v[238:241], v[138:141], v[14:17]
	v_mfma_f32_16x16x32_bf16 v[18:21], v[238:241], v[142:145], v[18:21]
	ds_read_b128 v[238:241], v207 offset:8192
	s_waitcnt lgkmcnt(3)
	v_mfma_f32_16x16x32_bf16 v[22:25], v[242:245], v[130:133], v[22:25]
	v_mfma_f32_16x16x32_bf16 v[26:29], v[242:245], v[134:137], v[26:29]
	v_mfma_f32_16x16x32_bf16 v[30:33], v[242:245], v[138:141], v[30:33]
	v_mfma_f32_16x16x32_bf16 v[34:37], v[242:245], v[142:145], v[34:37]
	ds_read_b128 v[242:245], v207 offset:10240
	s_waitcnt lgkmcnt(3)
	v_mfma_f32_16x16x32_bf16 v[38:41], v[246:249], v[130:133], v[38:41]
	v_mfma_f32_16x16x32_bf16 v[42:45], v[246:249], v[134:137], v[42:45]
	v_mfma_f32_16x16x32_bf16 v[46:49], v[246:249], v[138:141], v[46:49]
	v_mfma_f32_16x16x32_bf16 v[50:53], v[246:249], v[142:145], v[50:53]
	ds_read_b128 v[246:249], v207 offset:12288
	s_waitcnt lgkmcnt(3)
	v_mfma_f32_16x16x32_bf16 v[54:57], v[250:253], v[130:133], v[54:57]
	v_mfma_f32_16x16x32_bf16 v[58:61], v[250:253], v[134:137], v[58:61]
	v_mfma_f32_16x16x32_bf16 v[62:65], v[250:253], v[138:141], v[62:65]
	v_mfma_f32_16x16x32_bf16 v[66:69], v[250:253], v[142:145], v[66:69]
	ds_read_b128 v[250:253], v207 offset:14336
	s_waitcnt lgkmcnt(3)
	v_mfma_f32_16x16x32_bf16 v[70:73], v[238:241], v[130:133], v[70:73]
	v_mfma_f32_16x16x32_bf16 v[74:77], v[238:241], v[134:137], v[74:77]
	v_mfma_f32_16x16x32_bf16 v[78:81], v[238:241], v[138:141], v[78:81]
	v_mfma_f32_16x16x32_bf16 v[82:85], v[238:241], v[142:145], v[82:85]
	s_waitcnt lgkmcnt(2)
	v_mfma_f32_16x16x32_bf16 v[86:89], v[242:245], v[130:133], v[86:89]
	v_mfma_f32_16x16x32_bf16 v[90:93], v[242:245], v[134:137], v[90:93]
	v_mfma_f32_16x16x32_bf16 v[94:97], v[242:245], v[138:141], v[94:97]
	v_mfma_f32_16x16x32_bf16 v[98:101], v[242:245], v[142:145], v[98:101]
	s_waitcnt lgkmcnt(0)
	s_waitcnt vmcnt(0)
	s_add_i32 s48, s48, 1
	s_and_b32 s48, s48, 15
	s_lshl_b32 s2, s48, 7
	s_add_u32 s44, s40, s2
	s_addc_u32 s45, s41, 0
	s_add_u32 s42, s0, s2
	s_addc_u32 s43, s1, 0
	s_barrier
; #define GCOMPUTE(AS, BS) GCOMPUTE_KS(AS, BS, 0) GCOMPUTE_KS(AS, BS, 1)
; template <int EPI>
; DI void gemm_phase(const P& p, int l, const u16* __restrict__ A, const u16* __restrict__ Bt, int mpx, char* lds) {
;     ...
; #pragma unroll 1
;   for (int kk = 1; kk < 15; kk += 2) {
;     __syncthreads();
;     GSTORE(As0, Bs0)
;     GLOAD(Ag, Bg, (kk + 2) * 64)
;     __builtin_amdgcn_sched_barrier(0);
;     GCOMPUTE(As1, Bs1)
;     __builtin_amdgcn_sched_barrier(0);
	s_add_i32 m0, s47, 0x20
	s_nop 0
	global_load_lds_dwordx4 v162, s[44:45]
	s_add_i32 m0, s47, 0x2020
	s_nop 0
	global_load_lds_dwordx4 v163, s[44:45]
	s_add_i32 m0, s47, 0x4020
	s_nop 0
	global_load_lds_dwordx4 v164, s[44:45]
	s_add_i32 m0, s47, 0x6020
	s_nop 0
	global_load_lds_dwordx4 v165, s[44:45]
	s_add_i32 m0, s47, 0x8020
	s_nop 0
	global_load_lds_dwordx4 v162, s[42:43]
	s_add_i32 m0, s47, 0xa020
	s_nop 0
	global_load_lds_dwordx4 v163, s[42:43]
	s_add_i32 m0, s47, 0xc020
	s_nop 0
	global_load_lds_dwordx4 v164, s[42:43]
	s_add_i32 m0, s47, 0xe020
	s_nop 0
	global_load_lds_dwordx4 v165, s[42:43]
	ds_read_b128 v[212:215], v198
	ds_read_b128 v[216:219], v198 offset:2048
	ds_read_b128 v[220:223], v198 offset:4096
	ds_read_b128 v[234:237], v198 offset:6144
	ds_read_b128 v[238:241], v199
	ds_read_b128 v[242:245], v199 offset:2048
	v_mfma_f32_16x16x32_bf16 v[102:105], v[246:249], v[130:133], v[102:105]
	v_mfma_f32_16x16x32_bf16 v[106:109], v[246:249], v[134:137], v[106:109]
	v_mfma_f32_16x16x32_bf16 v[110:113], v[246:249], v[138:141], v[110:113]
	v_mfma_f32_16x16x32_bf16 v[114:117], v[246:249], v[142:145], v[114:117]
	ds_read_b128 v[246:249], v199 offset:4096
	v_mfma_f32_16x16x32_bf16 v[118:121], v[250:253], v[130:133], v[118:121]
	v_mfma_f32_16x16x32_bf16 v[122:125], v[250:253], v[134:137], v[122:125]
	v_mfma_f32_16x16x32_bf16 v[126:129], v[250:253], v[138:141], v[126:129]
	v_mfma_f32_16x16x32_bf16 v[2:5], v[250:253], v[142:145], v[2:5]
	ds_read_b128 v[250:253], v199 offset:6144
.LBB0_82:
	s_waitcnt lgkmcnt(3)
	v_mfma_f32_16x16x32_bf16 v[6:9], v[238:241], v[212:215], v[6:9]
	v_mfma_f32_16x16x32_bf16 v[10:13], v[238:241], v[216:219], v[10:13]
	v_mfma_f32_16x16x32_bf16 v[14:17], v[238:241], v[220:223], v[14:17]
	v_mfma_f32_16x16x32_bf16 v[18:21], v[238:241], v[234:237], v[18:21]
	ds_read_b128 v[238:241], v199 offset:8192
	s_waitcnt lgkmcnt(3)
	v_mfma_f32_16x16x32_bf16 v[22:25], v[242:245], v[212:215], v[22:25]
	v_mfma_f32_16x16x32_bf16 v[26:29], v[242:245], v[216:219], v[26:29]
	v_mfma_f32_16x16x32_bf16 v[30:33], v[242:245], v[220:223], v[30:33]
	v_mfma_f32_16x16x32_bf16 v[34:37], v[242:245], v[234:237], v[34:37]
	ds_read_b128 v[242:245], v199 offset:10240
	ds_read_b128 v[130:133], v200
	s_waitcnt lgkmcnt(4)
	v_mfma_f32_16x16x32_bf16 v[38:41], v[246:249], v[212:215], v[38:41]
	v_mfma_f32_16x16x32_bf16 v[42:45], v[246:249], v[216:219], v[42:45]
	v_mfma_f32_16x16x32_bf16 v[46:49], v[246:249], v[220:223], v[46:49]
	v_mfma_f32_16x16x32_bf16 v[50:53], v[246:249], v[234:237], v[50:53]
	ds_read_b128 v[246:249], v199 offset:12288
	ds_read_b128 v[134:137], v200 offset:2048
	s_waitcnt lgkmcnt(5)
	v_mfma_f32_16x16x32_bf16 v[54:57], v[250:253], v[212:215], v[54:57]
	v_mfma_f32_16x16x32_bf16 v[58:61], v[250:253], v[216:219], v[58:61]
	v_mfma_f32_16x16x32_bf16 v[62:65], v[250:253], v[220:223], v[62:65]
	v_mfma_f32_16x16x32_bf16 v[66:69], v[250:253], v[234:237], v[66:69]
	ds_read_b128 v[250:253], v199 offset:14336
	ds_read_b128 v[138:141], v200 offset:4096
	s_waitcnt lgkmcnt(6)
	v_mfma_f32_16x16x32_bf16 v[70:73], v[238:241], v[212:215], v[70:73]
	v_mfma_f32_16x16x32_bf16 v[74:77], v[238:241], v[216:219], v[74:77]
	v_mfma_f32_16x16x32_bf16 v[78:81], v[238:241], v[220:223], v[78:81]
	v_mfma_f32_16x16x32_bf16 v[82:85], v[238:241], v[234:237], v[82:85]
	ds_read_b128 v[238:241], v233
	ds_read_b128 v[142:145], v200 offset:6144
	s_waitcnt lgkmcnt(7)
	v_mfma_f32_16x16x32_bf16 v[86:89], v[242:245], v[212:215], v[86:89]
	v_mfma_f32_16x16x32_bf16 v[90:93], v[242:245], v[216:219], v[90:93]
	v_mfma_f32_16x16x32_bf16 v[94:97], v[242:245], v[220:223], v[94:97]
	v_mfma_f32_16x16x32_bf16 v[98:101], v[242:245], v[234:237], v[98:101]
	ds_read_b128 v[242:245], v233 offset:2048
	s_waitcnt lgkmcnt(6)
	v_mfma_f32_16x16x32_bf16 v[102:105], v[246:249], v[212:215], v[102:105]
	v_mfma_f32_16x16x32_bf16 v[106:109], v[246:249], v[216:219], v[106:109]
	v_mfma_f32_16x16x32_bf16 v[110:113], v[246:249], v[220:223], v[110:113]
	v_mfma_f32_16x16x32_bf16 v[114:117], v[246:249], v[234:237], v[114:117]
	ds_read_b128 v[246:249], v233 offset:4096
	s_waitcnt lgkmcnt(5)
	v_mfma_f32_16x16x32_bf16 v[118:121], v[250:253], v[212:215], v[118:121]
	v_mfma_f32_16x16x32_bf16 v[122:125], v[250:253], v[216:219], v[122:125]
	v_mfma_f32_16x16x32_bf16 v[126:129], v[250:253], v[220:223], v[126:129]
	v_mfma_f32_16x16x32_bf16 v[2:5], v[250:253], v[234:237], v[2:5]
	ds_read_b128 v[250:253], v233 offset:6144
	s_waitcnt lgkmcnt(3)
	v_mfma_f32_16x16x32_bf16 v[6:9], v[238:241], v[130:133], v[6:9]
	v_mfma_f32_16x16x32_bf16 v[10:13], v[238:241], v[134:137], v[10:13]
	v_mfma_f32_16x16x32_bf16 v[14:17], v[238:241], v[138:141], v[14:17]
	v_mfma_f32_16x16x32_bf16 v[18:21], v[238:241], v[142:145], v[18:21]
	ds_read_b128 v[238:241], v233 offset:8192
	s_waitcnt lgkmcnt(3)
	v_mfma_f32_16x16x32_bf16 v[22:25], v[242:245], v[130:133], v[22:25]
	v_mfma_f32_16x16x32_bf16 v[26:29], v[242:245], v[134:137], v[26:29]
	v_mfma_f32_16x16x32_bf16 v[30:33], v[242:245], v[138:141], v[30:33]
	v_mfma_f32_16x16x32_bf16 v[34:37], v[242:245], v[142:145], v[34:37]
	ds_read_b128 v[242:245], v233 offset:10240
	s_waitcnt lgkmcnt(3)
	v_mfma_f32_16x16x32_bf16 v[38:41], v[246:249], v[130:133], v[38:41]
	v_mfma_f32_16x16x32_bf16 v[42:45], v[246:249], v[134:137], v[42:45]
	v_mfma_f32_16x16x32_bf16 v[46:49], v[246:249], v[138:141], v[46:49]
	v_mfma_f32_16x16x32_bf16 v[50:53], v[246:249], v[142:145], v[50:53]
	ds_read_b128 v[246:249], v233 offset:12288
	s_waitcnt lgkmcnt(3)
	v_mfma_f32_16x16x32_bf16 v[54:57], v[250:253], v[130:133], v[54:57]
	v_mfma_f32_16x16x32_bf16 v[58:61], v[250:253], v[134:137], v[58:61]
	v_mfma_f32_16x16x32_bf16 v[62:65], v[250:253], v[138:141], v[62:65]
	v_mfma_f32_16x16x32_bf16 v[66:69], v[250:253], v[142:145], v[66:69]
	ds_read_b128 v[250:253], v233 offset:14336
	s_waitcnt lgkmcnt(3)
	v_mfma_f32_16x16x32_bf16 v[70:73], v[238:241], v[130:133], v[70:73]
	v_mfma_f32_16x16x32_bf16 v[74:77], v[238:241], v[134:137], v[74:77]
	v_mfma_f32_16x16x32_bf16 v[78:81], v[238:241], v[138:141], v[78:81]
	v_mfma_f32_16x16x32_bf16 v[82:85], v[238:241], v[142:145], v[82:85]
	s_waitcnt lgkmcnt(2)
	v_mfma_f32_16x16x32_bf16 v[86:89], v[242:245], v[130:133], v[86:89]
	v_mfma_f32_16x16x32_bf16 v[90:93], v[242:245], v[134:137], v[90:93]
	v_mfma_f32_16x16x32_bf16 v[94:97], v[242:245], v[138:141], v[94:97]
	v_mfma_f32_16x16x32_bf16 v[98:101], v[242:245], v[142:145], v[98:101]
	s_waitcnt lgkmcnt(0)
	s_waitcnt vmcnt(0)
	s_add_i32 s48, s48, 1
	s_and_b32 s48, s48, 15
	s_lshl_b32 s2, s48, 7
	s_add_u32 s44, s40, s2
	s_addc_u32 s45, s41, 0
	s_add_u32 s42, s0, s2
	s_addc_u32 s43, s1, 0
	s_barrier
; #define GCOMPUTE(AS, BS) GCOMPUTE_KS(AS, BS, 0) GCOMPUTE_KS(AS, BS, 1)
; template <int EPI>
; DI void gemm_phase(const P& p, int l, const u16* __restrict__ A, const u16* __restrict__ Bt, int mpx, char* lds) {
;     ...
;     __syncthreads();
;     GSTORE(As1, Bs1)
;     {
;       const bool in_tile = kk + 3 < 16;
;       const u16* pa = in_tile ? Ag : Agn;
;       const u16* pb = in_tile ? Bg : Bgn;
;       const int k0 = in_tile ? (kk + 3) * 64 : 0;
;       GLOAD(pa, pb, k0)
;     }
;     __builtin_amdgcn_sched_barrier(0);
;     GCOMPUTE(As0, Bs0)
;     __builtin_amdgcn_sched_barrier(0);
;   }
	s_add_i32 m0, s47, 0x10020
	s_nop 0
	global_load_lds_dwordx4 v162, s[44:45]
	s_add_i32 m0, s47, 0x12020
	s_nop 0
	global_load_lds_dwordx4 v163, s[44:45]
	s_add_i32 m0, s47, 0x14020
	s_nop 0
	global_load_lds_dwordx4 v164, s[44:45]
	s_add_i32 m0, s47, 0x16020
	s_nop 0
	global_load_lds_dwordx4 v165, s[44:45]
	s_add_i32 m0, s47, 0x18020
	s_nop 0
	global_load_lds_dwordx4 v162, s[42:43]
	s_add_i32 m0, s47, 0x1a020
	s_nop 0
	global_load_lds_dwordx4 v163, s[42:43]
	s_add_i32 m0, s47, 0x1c020
	s_nop 0
	global_load_lds_dwordx4 v164, s[42:43]
	s_add_i32 m0, s47, 0x1e020
	s_nop 0
	global_load_lds_dwordx4 v165, s[42:43]
	ds_read_b128 v[212:215], v204 offset:32768
	ds_read_b128 v[216:219], v204 offset:34816
	ds_read_b128 v[220:223], v204 offset:36864
	ds_read_b128 v[234:237], v204 offset:38912
	ds_read_b128 v[238:241], v205
	ds_read_b128 v[242:245], v205 offset:2048
	v_mfma_f32_16x16x32_bf16 v[102:105], v[246:249], v[130:133], v[102:105]
	v_mfma_f32_16x16x32_bf16 v[106:109], v[246:249], v[134:137], v[106:109]
	v_mfma_f32_16x16x32_bf16 v[110:113], v[246:249], v[138:141], v[110:113]
	v_mfma_f32_16x16x32_bf16 v[114:117], v[246:249], v[142:145], v[114:117]
	ds_read_b128 v[246:249], v205 offset:4096
	v_mfma_f32_16x16x32_bf16 v[118:121], v[250:253], v[130:133], v[118:121]
	v_mfma_f32_16x16x32_bf16 v[122:125], v[250:253], v[134:137], v[122:125]
	v_mfma_f32_16x16x32_bf16 v[126:129], v[250:253], v[138:141], v[126:129]
	v_mfma_f32_16x16x32_bf16 v[2:5], v[250:253], v[142:145], v[2:5]
	ds_read_b128 v[250:253], v205 offset:6144
	s_waitcnt lgkmcnt(3)
	v_mfma_f32_16x16x32_bf16 v[6:9], v[238:241], v[212:215], v[6:9]
	v_mfma_f32_16x16x32_bf16 v[10:13], v[238:241], v[216:219], v[10:13]
	v_mfma_f32_16x16x32_bf16 v[14:17], v[238:241], v[220:223], v[14:17]
	v_mfma_f32_16x16x32_bf16 v[18:21], v[238:241], v[234:237], v[18:21]
	ds_read_b128 v[238:241], v205 offset:8192
	s_waitcnt lgkmcnt(3)
	v_mfma_f32_16x16x32_bf16 v[22:25], v[242:245], v[212:215], v[22:25]
	v_mfma_f32_16x16x32_bf16 v[26:29], v[242:245], v[216:219], v[26:29]
	v_mfma_f32_16x16x32_bf16 v[30:33], v[242:245], v[220:223], v[30:33]
	v_mfma_f32_16x16x32_bf16 v[34:37], v[242:245], v[234:237], v[34:37]
	ds_read_b128 v[242:245], v205 offset:10240
	ds_read_b128 v[130:133], v206 offset:32768
	s_waitcnt lgkmcnt(4)
	v_mfma_f32_16x16x32_bf16 v[38:41], v[246:249], v[212:215], v[38:41]
	v_mfma_f32_16x16x32_bf16 v[42:45], v[246:249], v[216:219], v[42:45]
	v_mfma_f32_16x16x32_bf16 v[46:49], v[246:249], v[220:223], v[46:49]
	v_mfma_f32_16x16x32_bf16 v[50:53], v[246:249], v[234:237], v[50:53]
	ds_read_b128 v[246:249], v205 offset:12288
	ds_read_b128 v[134:137], v206 offset:34816
	s_waitcnt lgkmcnt(5)
	v_mfma_f32_16x16x32_bf16 v[54:57], v[250:253], v[212:215], v[54:57]
	v_mfma_f32_16x16x32_bf16 v[58:61], v[250:253], v[216:219], v[58:61]
	v_mfma_f32_16x16x32_bf16 v[62:65], v[250:253], v[220:223], v[62:65]
	v_mfma_f32_16x16x32_bf16 v[66:69], v[250:253], v[234:237], v[66:69]
	ds_read_b128 v[250:253], v205 offset:14336
	ds_read_b128 v[138:141], v206 offset:36864
	s_waitcnt lgkmcnt(6)
	v_mfma_f32_16x16x32_bf16 v[70:73], v[238:241], v[212:215], v[70:73]
	v_mfma_f32_16x16x32_bf16 v[74:77], v[238:241], v[216:219], v[74:77]
	v_mfma_f32_16x16x32_bf16 v[78:81], v[238:241], v[220:223], v[78:81]
	v_mfma_f32_16x16x32_bf16 v[82:85], v[238:241], v[234:237], v[82:85]
	ds_read_b128 v[238:241], v207
	ds_read_b128 v[142:145], v206 offset:38912
	s_waitcnt lgkmcnt(7)
	v_mfma_f32_16x16x32_bf16 v[86:89], v[242:245], v[212:215], v[86:89]
	v_mfma_f32_16x16x32_bf16 v[90:93], v[242:245], v[216:219], v[90:93]
	v_mfma_f32_16x16x32_bf16 v[94:97], v[242:245], v[220:223], v[94:97]
	v_mfma_f32_16x16x32_bf16 v[98:101], v[242:245], v[234:237], v[98:101]
	ds_read_b128 v[242:245], v207 offset:2048
	s_waitcnt lgkmcnt(6)
	v_mfma_f32_16x16x32_bf16 v[102:105], v[246:249], v[212:215], v[102:105]
	v_mfma_f32_16x16x32_bf16 v[106:109], v[246:249], v[216:219], v[106:109]
	v_mfma_f32_16x16x32_bf16 v[110:113], v[246:249], v[220:223], v[110:113]
	v_mfma_f32_16x16x32_bf16 v[114:117], v[246:249], v[234:237], v[114:117]
	ds_read_b128 v[246:249], v207 offset:4096
	s_waitcnt lgkmcnt(5)
	v_mfma_f32_16x16x32_bf16 v[118:121], v[250:253], v[212:215], v[118:121]
	v_mfma_f32_16x16x32_bf16 v[122:125], v[250:253], v[216:219], v[122:125]
	v_mfma_f32_16x16x32_bf16 v[126:129], v[250:253], v[220:223], v[126:129]
	v_mfma_f32_16x16x32_bf16 v[2:5], v[250:253], v[234:237], v[2:5]
	ds_read_b128 v[250:253], v207 offset:6144
	s_waitcnt lgkmcnt(3)
	v_mfma_f32_16x16x32_bf16 v[6:9], v[238:241], v[130:133], v[6:9]
	v_mfma_f32_16x16x32_bf16 v[10:13], v[238:241], v[134:137], v[10:13]
	v_mfma_f32_16x16x32_bf16 v[14:17], v[238:241], v[138:141], v[14:17]
	v_mfma_f32_16x16x32_bf16 v[18:21], v[238:241], v[142:145], v[18:21]
	ds_read_b128 v[238:241], v207 offset:8192
	s_waitcnt lgkmcnt(3)
	v_mfma_f32_16x16x32_bf16 v[22:25], v[242:245], v[130:133], v[22:25]
	v_mfma_f32_16x16x32_bf16 v[26:29], v[242:245], v[134:137], v[26:29]
	v_mfma_f32_16x16x32_bf16 v[30:33], v[242:245], v[138:141], v[30:33]
	v_mfma_f32_16x16x32_bf16 v[34:37], v[242:245], v[142:145], v[34:37]
	ds_read_b128 v[242:245], v207 offset:10240
	s_waitcnt lgkmcnt(3)
	v_mfma_f32_16x16x32_bf16 v[38:41], v[246:249], v[130:133], v[38:41]
	v_mfma_f32_16x16x32_bf16 v[42:45], v[246:249], v[134:137], v[42:45]
	v_mfma_f32_16x16x32_bf16 v[46:49], v[246:249], v[138:141], v[46:49]
	v_mfma_f32_16x16x32_bf16 v[50:53], v[246:249], v[142:145], v[50:53]
	ds_read_b128 v[246:249], v207 offset:12288
	s_waitcnt lgkmcnt(3)
	v_mfma_f32_16x16x32_bf16 v[54:57], v[250:253], v[130:133], v[54:57]
	v_mfma_f32_16x16x32_bf16 v[58:61], v[250:253], v[134:137], v[58:61]
	v_mfma_f32_16x16x32_bf16 v[62:65], v[250:253], v[138:141], v[62:65]
	v_mfma_f32_16x16x32_bf16 v[66:69], v[250:253], v[142:145], v[66:69]
	ds_read_b128 v[250:253], v207 offset:14336
	s_waitcnt lgkmcnt(3)
	v_mfma_f32_16x16x32_bf16 v[70:73], v[238:241], v[130:133], v[70:73]
	v_mfma_f32_16x16x32_bf16 v[74:77], v[238:241], v[134:137], v[74:77]
	v_mfma_f32_16x16x32_bf16 v[78:81], v[238:241], v[138:141], v[78:81]
	v_mfma_f32_16x16x32_bf16 v[82:85], v[238:241], v[142:145], v[82:85]
	s_waitcnt lgkmcnt(2)
	v_mfma_f32_16x16x32_bf16 v[86:89], v[242:245], v[130:133], v[86:89]
	v_mfma_f32_16x16x32_bf16 v[90:93], v[242:245], v[134:137], v[90:93]
	v_mfma_f32_16x16x32_bf16 v[94:97], v[242:245], v[138:141], v[94:97]
	v_mfma_f32_16x16x32_bf16 v[98:101], v[242:245], v[142:145], v[98:101]
	s_waitcnt lgkmcnt(0)
	s_waitcnt vmcnt(0)
	s_add_i32 s48, s48, 1
	s_and_b32 s48, s48, 15
	s_lshl_b32 s2, s48, 7
	s_add_u32 s44, s40, s2
	s_addc_u32 s45, s41, 0
	s_add_u32 s42, s0, s2
	s_addc_u32 s43, s1, 0
	s_add_i32 s49, s49, 1
	s_cmp_lt_u32 s49, 7
	s_cselect_b32 s44, s44, s62
	s_cselect_b32 s45, s45, s63
	s_cselect_b32 s42, s42, s64
	s_cselect_b32 s43, s43, s65
	s_barrier
; #define GCOMPUTE(AS, BS) GCOMPUTE_KS(AS, BS, 0) GCOMPUTE_KS(AS, BS, 1)
; template <int EPI>
; DI void gemm_phase(const P& p, int l, const u16* __restrict__ A, const u16* __restrict__ Bt, int mpx, char* lds) {
;     ...
;     {
;       const bool in_tile = kk + 3 < 16;
;       const u16* pa = in_tile ? Ag : Agn;
;       const u16* pb = in_tile ? Bg : Bgn;
;       const int k0 = in_tile ? (kk + 3) * 64 : 0;
;       GLOAD(pa, pb, k0)
;     }
;     __builtin_amdgcn_sched_barrier(0);
;     GCOMPUTE(As0, Bs0)
;     __builtin_amdgcn_sched_barrier(0);
	s_add_i32 m0, s47, 0x20
	s_nop 0
	global_load_lds_dwordx4 v162, s[44:45]
	s_add_i32 m0, s47, 0x2020
	s_nop 0
	global_load_lds_dwordx4 v163, s[44:45]
	s_add_i32 m0, s47, 0x4020
	s_nop 0
	global_load_lds_dwordx4 v164, s[44:45]
	s_add_i32 m0, s47, 0x6020
	s_nop 0
	global_load_lds_dwordx4 v165, s[44:45]
	s_add_i32 m0, s47, 0x8020
	s_nop 0
	global_load_lds_dwordx4 v162, s[42:43]
	s_add_i32 m0, s47, 0xa020
	s_nop 0
	global_load_lds_dwordx4 v163, s[42:43]
	s_add_i32 m0, s47, 0xc020
	s_nop 0
	global_load_lds_dwordx4 v164, s[42:43]
	s_add_i32 m0, s47, 0xe020
	s_nop 0
	global_load_lds_dwordx4 v165, s[42:43]
	ds_read_b128 v[212:215], v198
	ds_read_b128 v[216:219], v198 offset:2048
	ds_read_b128 v[220:223], v198 offset:4096
	ds_read_b128 v[234:237], v198 offset:6144
	ds_read_b128 v[238:241], v199
	ds_read_b128 v[242:245], v199 offset:2048
	v_mfma_f32_16x16x32_bf16 v[102:105], v[246:249], v[130:133], v[102:105]
	v_mfma_f32_16x16x32_bf16 v[106:109], v[246:249], v[134:137], v[106:109]
	v_mfma_f32_16x16x32_bf16 v[110:113], v[246:249], v[138:141], v[110:113]
	v_mfma_f32_16x16x32_bf16 v[114:117], v[246:249], v[142:145], v[114:117]
	ds_read_b128 v[246:249], v199 offset:4096
	v_mfma_f32_16x16x32_bf16 v[118:121], v[250:253], v[130:133], v[118:121]
	v_mfma_f32_16x16x32_bf16 v[122:125], v[250:253], v[134:137], v[122:125]
	v_mfma_f32_16x16x32_bf16 v[126:129], v[250:253], v[138:141], v[126:129]
	v_mfma_f32_16x16x32_bf16 v[2:5], v[250:253], v[142:145], v[2:5]
	ds_read_b128 v[250:253], v199 offset:6144
	s_cmp_lt_u32 s49, 7
	s_cbranch_scc1 .LBB0_82
; template <int EPI>
; DI void gemm_phase(const P& p, int l, const u16* __restrict__ A, const u16* __restrict__ Bt, int mpx, char* lds) {
;     ...
;     const int cb = n0 + wn * 64;
;     const bool isctx = m0 >= MLAT;
;     const int b = isctx ? ((m0 - MLAT) >> 8) : (m0 >> 11);
;     const int tokw = (isctx ? 2048 + ((m0 - MLAT) & 255) : (m0 & 2047)) + wm * 128;
;     u16* Tl = (u16*)(lds + 65536) + w * (64 * 72);
;     int kind = 0;
;     int tr = 0;
;     bool donorm = false;
;     if (cb >= 2816) { kind = 2; tr = 1; }
;     else if (cb < 256) tr = 1;
;     else if (cb < 512) tr = 0;
;     else if (cb < 1024) tr = 2;
;     else if (cb < 1408) { tr = 3; donorm = true; }
;     else if (cb < 1536) kind = 1;
;     else if (cb < 2048) tr = isctx ? 0 : 4;
;     else if (cb < 2304) kind = 1;
;     else if (cb < 2688) tr = isctx ? 0 : 3;
;     else kind = 1;
	s_waitcnt lgkmcnt(3)
	v_mfma_f32_16x16x32_bf16 v[6:9], v[238:241], v[212:215], v[6:9]
	v_mfma_f32_16x16x32_bf16 v[10:13], v[238:241], v[216:219], v[10:13]
	v_mfma_f32_16x16x32_bf16 v[14:17], v[238:241], v[220:223], v[14:17]
	v_mfma_f32_16x16x32_bf16 v[18:21], v[238:241], v[234:237], v[18:21]
	ds_read_b128 v[238:241], v199 offset:8192
	s_waitcnt lgkmcnt(3)
	v_mfma_f32_16x16x32_bf16 v[22:25], v[242:245], v[212:215], v[22:25]
	v_mfma_f32_16x16x32_bf16 v[26:29], v[242:245], v[216:219], v[26:29]
	v_mfma_f32_16x16x32_bf16 v[30:33], v[242:245], v[220:223], v[30:33]
	v_mfma_f32_16x16x32_bf16 v[34:37], v[242:245], v[234:237], v[34:37]
	ds_read_b128 v[242:245], v199 offset:10240
	ds_read_b128 v[130:133], v200
	s_waitcnt lgkmcnt(4)
	v_mfma_f32_16x16x32_bf16 v[38:41], v[246:249], v[212:215], v[38:41]
	v_mfma_f32_16x16x32_bf16 v[42:45], v[246:249], v[216:219], v[42:45]
	v_mfma_f32_16x16x32_bf16 v[46:49], v[246:249], v[220:223], v[46:49]
	v_mfma_f32_16x16x32_bf16 v[50:53], v[246:249], v[234:237], v[50:53]
	ds_read_b128 v[246:249], v199 offset:12288
	ds_read_b128 v[134:137], v200 offset:2048
	s_waitcnt lgkmcnt(5)
	v_mfma_f32_16x16x32_bf16 v[54:57], v[250:253], v[212:215], v[54:57]
	v_mfma_f32_16x16x32_bf16 v[58:61], v[250:253], v[216:219], v[58:61]
	v_mfma_f32_16x16x32_bf16 v[62:65], v[250:253], v[220:223], v[62:65]
	v_mfma_f32_16x16x32_bf16 v[66:69], v[250:253], v[234:237], v[66:69]
	ds_read_b128 v[250:253], v199 offset:14336
	ds_read_b128 v[138:141], v200 offset:4096
	s_waitcnt lgkmcnt(6)
	v_mfma_f32_16x16x32_bf16 v[70:73], v[238:241], v[212:215], v[70:73]
	v_mfma_f32_16x16x32_bf16 v[74:77], v[238:241], v[216:219], v[74:77]
	v_mfma_f32_16x16x32_bf16 v[78:81], v[238:241], v[220:223], v[78:81]
	v_mfma_f32_16x16x32_bf16 v[82:85], v[238:241], v[234:237], v[82:85]
	ds_read_b128 v[238:241], v233
	ds_read_b128 v[142:145], v200 offset:6144
	s_waitcnt lgkmcnt(7)
	v_mfma_f32_16x16x32_bf16 v[86:89], v[242:245], v[212:215], v[86:89]
	v_mfma_f32_16x16x32_bf16 v[90:93], v[242:245], v[216:219], v[90:93]
	v_mfma_f32_16x16x32_bf16 v[94:97], v[242:245], v[220:223], v[94:97]
	v_mfma_f32_16x16x32_bf16 v[98:101], v[242:245], v[234:237], v[98:101]
	ds_read_b128 v[242:245], v233 offset:2048
	s_waitcnt lgkmcnt(6)
	v_mfma_f32_16x16x32_bf16 v[102:105], v[246:249], v[212:215], v[102:105]
	v_mfma_f32_16x16x32_bf16 v[106:109], v[246:249], v[216:219], v[106:109]
	v_mfma_f32_16x16x32_bf16 v[110:113], v[246:249], v[220:223], v[110:113]
	v_mfma_f32_16x16x32_bf16 v[114:117], v[246:249], v[234:237], v[114:117]
	ds_read_b128 v[246:249], v233 offset:4096
	s_waitcnt lgkmcnt(5)
	v_mfma_f32_16x16x32_bf16 v[118:121], v[250:253], v[212:215], v[118:121]
	v_mfma_f32_16x16x32_bf16 v[122:125], v[250:253], v[216:219], v[122:125]
	v_mfma_f32_16x16x32_bf16 v[126:129], v[250:253], v[220:223], v[126:129]
	v_mfma_f32_16x16x32_bf16 v[2:5], v[250:253], v[234:237], v[2:5]
	ds_read_b128 v[250:253], v233 offset:6144
	s_waitcnt lgkmcnt(3)
	v_mfma_f32_16x16x32_bf16 v[6:9], v[238:241], v[130:133], v[6:9]
	v_mfma_f32_16x16x32_bf16 v[10:13], v[238:241], v[134:137], v[10:13]
	v_mfma_f32_16x16x32_bf16 v[14:17], v[238:241], v[138:141], v[14:17]
	v_mfma_f32_16x16x32_bf16 v[18:21], v[238:241], v[142:145], v[18:21]
	ds_read_b128 v[238:241], v233 offset:8192
	s_waitcnt lgkmcnt(3)
	v_mfma_f32_16x16x32_bf16 v[22:25], v[242:245], v[130:133], v[22:25]
	v_mfma_f32_16x16x32_bf16 v[26:29], v[242:245], v[134:137], v[26:29]
	v_mfma_f32_16x16x32_bf16 v[30:33], v[242:245], v[138:141], v[30:33]
	v_mfma_f32_16x16x32_bf16 v[34:37], v[242:245], v[142:145], v[34:37]
	ds_read_b128 v[242:245], v233 offset:10240
	s_waitcnt lgkmcnt(3)
	v_mfma_f32_16x16x32_bf16 v[38:41], v[246:249], v[130:133], v[38:41]
	v_mfma_f32_16x16x32_bf16 v[42:45], v[246:249], v[134:137], v[42:45]
	v_mfma_f32_16x16x32_bf16 v[46:49], v[246:249], v[138:141], v[46:49]
	v_mfma_f32_16x16x32_bf16 v[50:53], v[246:249], v[142:145], v[50:53]
	ds_read_b128 v[246:249], v233 offset:12288
	s_waitcnt lgkmcnt(3)
	v_mfma_f32_16x16x32_bf16 v[54:57], v[250:253], v[130:133], v[54:57]
	v_mfma_f32_16x16x32_bf16 v[58:61], v[250:253], v[134:137], v[58:61]
	v_mfma_f32_16x16x32_bf16 v[62:65], v[250:253], v[138:141], v[62:65]
	v_mfma_f32_16x16x32_bf16 v[66:69], v[250:253], v[142:145], v[66:69]
	ds_read_b128 v[250:253], v233 offset:14336
	s_waitcnt lgkmcnt(3)
	v_mfma_f32_16x16x32_bf16 v[70:73], v[238:241], v[130:133], v[70:73]
	v_mfma_f32_16x16x32_bf16 v[74:77], v[238:241], v[134:137], v[74:77]
	v_mfma_f32_16x16x32_bf16 v[78:81], v[238:241], v[138:141], v[78:81]
	v_mfma_f32_16x16x32_bf16 v[82:85], v[238:241], v[142:145], v[82:85]
	s_waitcnt lgkmcnt(2)
	v_mfma_f32_16x16x32_bf16 v[86:89], v[242:245], v[130:133], v[86:89]
	v_mfma_f32_16x16x32_bf16 v[90:93], v[242:245], v[134:137], v[90:93]
	v_mfma_f32_16x16x32_bf16 v[94:97], v[242:245], v[138:141], v[94:97]
	v_mfma_f32_16x16x32_bf16 v[98:101], v[242:245], v[142:145], v[98:101]
	s_waitcnt lgkmcnt(0)
	s_waitcnt vmcnt(0)
	s_barrier
	v_mfma_f32_16x16x32_bf16 v[102:105], v[246:249], v[130:133], v[102:105]
	v_mfma_f32_16x16x32_bf16 v[106:109], v[246:249], v[134:137], v[106:109]
	v_mfma_f32_16x16x32_bf16 v[110:113], v[246:249], v[138:141], v[110:113]
	v_mfma_f32_16x16x32_bf16 v[114:117], v[246:249], v[142:145], v[114:117]
	v_mfma_f32_16x16x32_bf16 v[118:121], v[250:253], v[130:133], v[118:121]
	v_mfma_f32_16x16x32_bf16 v[122:125], v[250:253], v[134:137], v[122:125]
	v_mfma_f32_16x16x32_bf16 v[126:129], v[250:253], v[138:141], v[126:129]
	v_mfma_f32_16x16x32_bf16 v[2:5], v[250:253], v[142:145], v[2:5]
	s_nop 0
	v_readfirstlane_b32 s40, v195
	s_lshr_b32 s40, s40, 6
	s_and_b32 s41, s40, 3
	s_lshr_b32 s42, s40, 2
	s_lshr_b32 s43, s46, 6
	s_add_i32 s43, s43, s41
	s_cmp_ge_u32 s66, 0x8000
	s_cselect_b32 s67, 1, 0
	s_mov_b32 s44, 0xffff
	s_mov_b32 s45, 0
	s_bitcmp1_b64 s[44:45], s43
	s_cbranch_scc1 .Lfe_kind0
	s_mov_b32 s44, 0xc00000
	s_mov_b32 s45, 0xc0f
	s_bitcmp1_b64 s[44:45], s43
	s_cbranch_scc1 .Lfe_kind1
	s_cmp_ge_u32 s43, 44
	s_cbranch_scc1 .Lfe_kind2
	s_branch .Lfe_kind0
